# lean in-proj slabs: no lgkmcnt wait between a wave's own slab writes and reads (in-order LDS)
# speedup vs baseline: 1.0006x; 1.0006x over previous
.LBB0_220:
	s_cmp_gt_i32 s7, 0
	s_waitcnt vmcnt(6)
	s_cselect_b32 s8, -1, 2
	s_mul_i32 s9, s7, 0x6000
	s_waitcnt lgkmcnt(0)
	s_add_i32 s8, s8, s7
	v_add_u32_e32 v139, s9, v224
	v_add_u32_e32 v0, s9, v223
	s_mulk_i32 s8, 0x6000
	v_add_u32_e32 v154, v139, v228
	s_barrier
	v_lshl_add_u64 v[170:171], v[144:145], 0, s[2:3]
	v_add_u32_e32 v141, s8, v221
	v_lshl_add_u64 v[174:175], v[142:143], 0, s[2:3]
	v_add_u32_e32 v182, s8, v222
	v_add_u32_e32 v166, v0, v228
	ds_read_b128 v[146:149], v166
	ds_read_b128 v[150:153], v154
	ds_read_b128 v[154:157], v154 offset:2048
	v_lshl_add_u64 v[172:173], v[170:171], 0, s[88:89]
	v_lshl_add_u64 v[176:177], v[174:175], 0, s[88:89]
	v_add_u32_e32 v183, 0x4000, v182
	v_lshl_add_u64 v[178:179], v[170:171], 0, s[90:91]
	v_add_u32_e32 v184, 0x400, v141
	v_lshl_add_u64 v[180:181], v[170:171], 0, s[78:79]
	v_add_u32_e32 v185, 0x800, v141
	ds_read_b128 v[158:161], v166 offset:2048
	ds_read_b128 v[162:165], v166 offset:4096
	ds_read_b128 v[166:169], v166 offset:6144
	s_waitcnt lgkmcnt(3)
	s_setprio 1
	v_mfma_f32_32x32x16_bf16 v[114:129], v[146:149], v[150:153], v[114:129]
	v_mfma_f32_32x32x16_bf16 v[98:113], v[146:149], v[154:157], v[98:113]
	v_readfirstlane_b32 s8, v141
	s_mov_b32 m0, s8
	s_nop 0
	global_load_lds_dwordx4 v[172:173], off
	s_waitcnt lgkmcnt(2)
	v_mfma_f32_32x32x16_bf16 v[82:97], v[158:161], v[150:153], v[82:97]
	v_mfma_f32_32x32x16_bf16 v[66:81], v[158:161], v[154:157], v[66:81]
	v_readfirstlane_b32 s8, v184
	s_mov_b32 m0, s8
	s_nop 0
	global_load_lds_dwordx4 v[178:179], off
	s_waitcnt lgkmcnt(1)
	v_mfma_f32_32x32x16_bf16 v[50:65], v[162:165], v[150:153], v[50:65]
	v_mfma_f32_32x32x16_bf16 v[34:49], v[162:165], v[154:157], v[34:49]
	v_readfirstlane_b32 s8, v185
	s_mov_b32 m0, s8
	s_nop 0
	global_load_lds_dwordx4 v[180:181], off
	s_waitcnt lgkmcnt(0)
	v_mfma_f32_32x32x16_bf16 v[18:33], v[166:169], v[150:153], v[18:33]
	v_mfma_f32_32x32x16_bf16 v[2:17], v[166:169], v[154:157], v[2:17]
	s_setprio 0
	v_add_u32_e32 v0, v0, v229
	v_add_u32_e32 v139, v139, v229
	ds_read_b128 v[146:149], v0
	ds_read_b128 v[150:153], v139
	ds_read_b128 v[154:157], v139 offset:2048
	ds_read_b128 v[158:161], v0 offset:2048
	ds_read_b128 v[162:165], v0 offset:4096
	ds_read_b128 v[166:169], v0 offset:6144
	s_waitcnt lgkmcnt(3)
	s_setprio 1
	v_mfma_f32_32x32x16_bf16 v[114:129], v[146:149], v[150:153], v[114:129]
	v_mfma_f32_32x32x16_bf16 v[98:113], v[146:149], v[154:157], v[98:113]
	v_add_u32_e32 v0, 0xc00, v141
	v_lshl_add_u64 v[146:147], v[170:171], 0, s[76:77]
	v_readfirstlane_b32 s8, v0
	s_mov_b32 m0, s8
	s_nop 0
	global_load_lds_dwordx4 v[146:147], off
	s_waitcnt lgkmcnt(2)
	v_mfma_f32_32x32x16_bf16 v[82:97], v[158:161], v[150:153], v[82:97]
	v_mfma_f32_32x32x16_bf16 v[66:81], v[158:161], v[154:157], v[66:81]
	v_readfirstlane_b32 s8, v183
	s_mov_b32 m0, s8
	s_nop 0
	global_load_lds_dwordx4 v[176:177], off
	s_waitcnt lgkmcnt(1)
	v_mfma_f32_32x32x16_bf16 v[50:65], v[162:165], v[150:153], v[50:65]
	v_mfma_f32_32x32x16_bf16 v[34:49], v[162:165], v[154:157], v[34:49]
	v_add_u32_e32 v0, 0x4400, v182
	v_lshl_add_u64 v[146:147], v[174:175], 0, s[90:91]
	v_readfirstlane_b32 s8, v0
	s_mov_b32 m0, s8
	s_nop 0
	global_load_lds_dwordx4 v[146:147], off
	s_waitcnt lgkmcnt(0)
	v_mfma_f32_32x32x16_bf16 v[18:33], v[166:169], v[150:153], v[18:33]
	v_mfma_f32_32x32x16_bf16 v[2:17], v[166:169], v[154:157], v[2:17]
	s_setprio 0
	s_add_i32 s8, s7, 1
	s_cmp_lt_i32 s7, 2
	s_cselect_b32 s7, s8, 0
	s_add_u32 s2, s2, 0x80
	s_addc_u32 s3, s3, 0
	s_cmpk_eq_i32 s2, 0xf00
	s_cbranch_scc0 .LBB0_220
	s_waitcnt vmcnt(6)
	s_mul_i32 s2, s7, 0x6000
	s_waitcnt lgkmcnt(0)
	v_add_u32_e32 v139, s2, v224
	v_add_u32_e32 v0, s2, v223
	v_add_u32_e32 v150, v139, v228
	s_barrier
	v_add_u32_e32 v141, v0, v228
	ds_read_b128 v[142:145], v141
	ds_read_b128 v[146:149], v150
	ds_read_b128 v[150:153], v150 offset:2048
	ds_read_b128 v[154:157], v141 offset:2048
	ds_read_b128 v[158:161], v141 offset:4096
	ds_read_b128 v[162:165], v141 offset:6144
	s_waitcnt lgkmcnt(3)
	s_setprio 1
	v_mfma_f32_32x32x16_bf16 v[114:129], v[142:145], v[146:149], v[114:129]
	v_mfma_f32_32x32x16_bf16 v[98:113], v[142:145], v[150:153], v[98:113]
	s_waitcnt lgkmcnt(2)
	v_mfma_f32_32x32x16_bf16 v[82:97], v[154:157], v[146:149], v[82:97]
	v_mfma_f32_32x32x16_bf16 v[66:81], v[154:157], v[150:153], v[66:81]
	s_waitcnt lgkmcnt(1)
	v_mfma_f32_32x32x16_bf16 v[50:65], v[158:161], v[146:149], v[50:65]
	v_mfma_f32_32x32x16_bf16 v[34:49], v[158:161], v[150:153], v[34:49]
	s_waitcnt lgkmcnt(0)
	v_mfma_f32_32x32x16_bf16 v[18:33], v[162:165], v[146:149], v[18:33]
	v_mfma_f32_32x32x16_bf16 v[2:17], v[162:165], v[150:153], v[2:17]
	s_setprio 0
	v_add_u32_e32 v0, v0, v229
	v_add_u32_e32 v139, v139, v229
	ds_read_b128 v[142:145], v0
	ds_read_b128 v[146:149], v139
	ds_read_b128 v[150:153], v139 offset:2048
	ds_read_b128 v[154:157], v0 offset:2048
	ds_read_b128 v[158:161], v0 offset:4096
	ds_read_b128 v[162:165], v0 offset:6144
	s_waitcnt lgkmcnt(3)
	s_setprio 1
	v_mfma_f32_32x32x16_bf16 v[114:129], v[142:145], v[146:149], v[114:129]
	v_mfma_f32_32x32x16_bf16 v[98:113], v[142:145], v[150:153], v[98:113]
	s_waitcnt lgkmcnt(2)
	v_mfma_f32_32x32x16_bf16 v[82:97], v[154:157], v[146:149], v[82:97]
	v_mfma_f32_32x32x16_bf16 v[66:81], v[154:157], v[150:153], v[66:81]
	s_waitcnt lgkmcnt(1)
	v_mfma_f32_32x32x16_bf16 v[50:65], v[158:161], v[146:149], v[50:65]
	v_mfma_f32_32x32x16_bf16 v[34:49], v[158:161], v[150:153], v[34:49]
	s_waitcnt lgkmcnt(0)
	v_mfma_f32_32x32x16_bf16 v[18:33], v[162:165], v[146:149], v[18:33]
	v_mfma_f32_32x32x16_bf16 v[2:17], v[162:165], v[150:153], v[2:17]
	s_setprio 0
	s_waitcnt vmcnt(0)
	s_waitcnt lgkmcnt(0)
	s_barrier
	ds_read_b128 v[142:145], v232
	ds_read_b128 v[146:149], v233
	ds_read_b128 v[150:153], v233 offset:2048
	ds_read_b128 v[154:157], v232 offset:2048
	ds_read_b128 v[158:161], v232 offset:4096
	ds_read_b128 v[162:165], v232 offset:6144
	s_waitcnt lgkmcnt(3)
	s_setprio 1
	v_mfma_f32_32x32x16_bf16 v[114:129], v[142:145], v[146:149], v[114:129]
	v_mfma_f32_32x32x16_bf16 v[98:113], v[142:145], v[150:153], v[98:113]
	s_waitcnt lgkmcnt(2)
	v_mfma_f32_32x32x16_bf16 v[82:97], v[154:157], v[146:149], v[82:97]
	v_mfma_f32_32x32x16_bf16 v[66:81], v[154:157], v[150:153], v[66:81]
	s_waitcnt lgkmcnt(1)
	v_mfma_f32_32x32x16_bf16 v[50:65], v[158:161], v[146:149], v[50:65]
	v_mfma_f32_32x32x16_bf16 v[34:49], v[158:161], v[150:153], v[34:49]
	s_waitcnt lgkmcnt(0)
	v_mfma_f32_32x32x16_bf16 v[18:33], v[162:165], v[146:149], v[18:33]
	v_mfma_f32_32x32x16_bf16 v[2:17], v[162:165], v[150:153], v[2:17]
	s_setprio 0
	ds_read_b128 v[142:145], v234
	ds_read_b128 v[146:149], v235
	ds_read_b128 v[150:153], v235 offset:2048
	ds_read_b128 v[154:157], v234 offset:2048
	ds_read_b128 v[158:161], v234 offset:4096
	ds_read_b128 v[162:165], v234 offset:6144
	s_waitcnt lgkmcnt(3)
	s_setprio 1
	v_mfma_f32_32x32x16_bf16 v[114:129], v[142:145], v[146:149], v[114:129]
	v_mfma_f32_32x32x16_bf16 v[98:113], v[142:145], v[150:153], v[98:113]
	s_waitcnt lgkmcnt(2)
	v_mfma_f32_32x32x16_bf16 v[82:97], v[154:157], v[146:149], v[82:97]
	v_mfma_f32_32x32x16_bf16 v[66:81], v[154:157], v[150:153], v[66:81]
	s_waitcnt lgkmcnt(1)
	v_mfma_f32_32x32x16_bf16 v[50:65], v[158:161], v[146:149], v[50:65]
	v_mfma_f32_32x32x16_bf16 v[34:49], v[158:161], v[150:153], v[34:49]
	s_waitcnt lgkmcnt(0)
	v_mfma_f32_32x32x16_bf16 v[18:33], v[162:165], v[146:149], v[18:33]
	v_mfma_f32_32x32x16_bf16 v[2:17], v[162:165], v[150:153], v[2:17]
	s_setprio 0
	s_cmp_gt_i32 s4, 3
	s_cselect_b64 s[30:31], -1, 0
	s_add_i32 s2, s4, -8
	s_cmp_gt_u32 s2, 5
	s_cselect_b64 s[98:99], -1, 0
	s_and_b32 s2, s4, 0x7ffffffc
	s_cmp_lg_u32 s2, 20
	v_add_u32_e32 v238, s5, v225
	s_cselect_b64 s[2:3], -1, 0
	s_and_b32 s5, s4, 0x7ffffffe
	s_cmp_eq_u32 s5, 6
	s_cselect_b64 s[82:83], -1, 0
	s_sub_i32 s5, s4, 17
	v_add_u32_e32 v239, 0x800, v230
	v_add_u32_e32 v240, 0x1000, v230
	v_add_u32_e32 v241, 0x1800, v230
	s_mov_b32 s8, 0x0701c030
	s_mov_b32 s34, 0x380e00c0
	s_lshr_b32 s8, s8, s4
	s_lshr_b32 s34, s34, s4
	s_and_b32 s8, s8, 1
	s_and_b32 s34, s34, 1
	s_or_b32 s7, s8, s34
	s_cmp_eq_u32 s7, 0
	s_cbranch_scc1 .Lmy_g0e_std
	v_and_b32_e32 v151, 63, v200
	v_lshrrev_b32_e32 v150, 5, v151
	v_and_b32_e32 v146, 31, v151
	v_lshrrev_b32_e32 v147, 6, v200
	v_lshrrev_b32_e32 v152, 1, v147
	v_and_b32_e32 v148, 1, v147
	v_mul_u32_u24_e32 v147, 0x2200, v147
	s_movk_i32 s6, 0x7c00
	v_mad_u32_u24 v147, v152, s6, v147
	v_lshlrev_b32_e32 v146, 2, v146
	s_movk_i32 s6, 0x440
	v_mad_u32_u24 v146, v150, s6, v146
	v_add_u32_e32 v146, v146, v147
	v_lshrrev_b32_e32 v150, 3, v151
	v_and_b32_e32 v149, 7, v151
	s_movk_i32 s6, 0x110
	v_mad_u32_u24 v147, v150, s6, v147
	v_lshl_add_u32 v147, v149, 5, v147
	v_lshl_add_u32 v152, v152, 7, s32
	v_add_u32_e32 v152, v152, v150
	s_lshl_b32 s6, s4, 7
	v_lshl_add_u32 v148, v148, 6, s6
	v_lshl_add_u32 v148, v149, 3, v148
	v_lshlrev_b32_e32 v148, 1, v148
	v_mul_u32_u24_e32 v152, 0x1e00, v152
	v_add_u32_e32 v148, v148, v152
	s_mov_b64 s[8:9], s[64:65]
	s_cmp_eq_u32 s34, 1
	s_cbranch_scc1 .Lmy_g0e_gate
	ds_write2_b32 v146, v114, v98 offset0:0 offset1:32
	ds_write2_b32 v146, v115, v99 offset0:68 offset1:100
	ds_write2_b32 v146, v116, v100 offset0:136 offset1:168
	ds_write2_b32 v146, v117, v101 offset0:204 offset1:236
	v_add_u32_e32 v146, 0x880, v146
	ds_write2_b32 v146, v118, v102 offset0:0 offset1:32
	ds_write2_b32 v146, v119, v103 offset0:68 offset1:100
	ds_write2_b32 v146, v120, v104 offset0:136 offset1:168
	ds_write2_b32 v146, v121, v105 offset0:204 offset1:236
	v_add_u32_e32 v146, 0x880, v146
	ds_write2_b32 v146, v122, v106 offset0:0 offset1:32
	ds_write2_b32 v146, v123, v107 offset0:68 offset1:100
	ds_write2_b32 v146, v124, v108 offset0:136 offset1:168
	ds_write2_b32 v146, v125, v109 offset0:204 offset1:236
	v_add_u32_e32 v146, 0x880, v146
	ds_write2_b32 v146, v126, v110 offset0:0 offset1:32
	ds_write2_b32 v146, v127, v111 offset0:68 offset1:100
	ds_write2_b32 v146, v128, v112 offset0:136 offset1:168
	ds_write2_b32 v146, v129, v113 offset0:204 offset1:236
	v_subrev_u32_e32 v146, 0x1980, v146
	ds_read_b128 v[98:101], v147
	ds_read_b128 v[102:105], v147 offset:16
	ds_read_b128 v[106:109], v147 offset:2176
	ds_read_b128 v[110:113], v147 offset:2192
	ds_read_b128 v[114:117], v147 offset:4352
	ds_read_b128 v[118:121], v147 offset:4368
	ds_read_b128 v[122:125], v147 offset:6528
	ds_read_b128 v[126:129], v147 offset:6544
	s_waitcnt lgkmcnt(6)
	v_cvt_pk_bf16_f32 v154, v98, v99
	v_cvt_pk_bf16_f32 v155, v100, v101
	v_cvt_pk_bf16_f32 v156, v102, v103
	v_cvt_pk_bf16_f32 v157, v104, v105
	global_store_dwordx4 v148, v[154:157], s[8:9]
	s_add_u32 s8, s8, 0xf000
	s_addc_u32 s9, s9, 0
	s_waitcnt lgkmcnt(4)
	v_cvt_pk_bf16_f32 v158, v106, v107
	v_cvt_pk_bf16_f32 v159, v108, v109
	v_cvt_pk_bf16_f32 v160, v110, v111
	v_cvt_pk_bf16_f32 v161, v112, v113
	global_store_dwordx4 v148, v[158:161], s[8:9]
	s_add_u32 s8, s8, 0xf000
	s_addc_u32 s9, s9, 0
	s_waitcnt lgkmcnt(2)
	v_cvt_pk_bf16_f32 v162, v114, v115
	v_cvt_pk_bf16_f32 v163, v116, v117
	v_cvt_pk_bf16_f32 v164, v118, v119
	v_cvt_pk_bf16_f32 v165, v120, v121
	global_store_dwordx4 v148, v[162:165], s[8:9]
	s_add_u32 s8, s8, 0xf000
	s_addc_u32 s9, s9, 0
	s_waitcnt lgkmcnt(0)
	v_cvt_pk_bf16_f32 v166, v122, v123
	v_cvt_pk_bf16_f32 v167, v124, v125
	v_cvt_pk_bf16_f32 v168, v126, v127
	v_cvt_pk_bf16_f32 v169, v128, v129
	global_store_dwordx4 v148, v[166:169], s[8:9]
	s_add_u32 s8, s8, 0xf000
	s_addc_u32 s9, s9, 0
	ds_write2_b32 v146, v82, v66 offset0:0 offset1:32
	ds_write2_b32 v146, v83, v67 offset0:68 offset1:100
	ds_write2_b32 v146, v84, v68 offset0:136 offset1:168
	ds_write2_b32 v146, v85, v69 offset0:204 offset1:236
	v_add_u32_e32 v146, 0x880, v146
	ds_write2_b32 v146, v86, v70 offset0:0 offset1:32
	ds_write2_b32 v146, v87, v71 offset0:68 offset1:100
	ds_write2_b32 v146, v88, v72 offset0:136 offset1:168
	ds_write2_b32 v146, v89, v73 offset0:204 offset1:236
	v_add_u32_e32 v146, 0x880, v146
	ds_write2_b32 v146, v90, v74 offset0:0 offset1:32
	ds_write2_b32 v146, v91, v75 offset0:68 offset1:100
	ds_write2_b32 v146, v92, v76 offset0:136 offset1:168
	ds_write2_b32 v146, v93, v77 offset0:204 offset1:236
	v_add_u32_e32 v146, 0x880, v146
	ds_write2_b32 v146, v94, v78 offset0:0 offset1:32
	ds_write2_b32 v146, v95, v79 offset0:68 offset1:100
	ds_write2_b32 v146, v96, v80 offset0:136 offset1:168
	ds_write2_b32 v146, v97, v81 offset0:204 offset1:236
	v_subrev_u32_e32 v146, 0x1980, v146
	ds_read_b128 v[66:69], v147
	ds_read_b128 v[70:73], v147 offset:16
	ds_read_b128 v[74:77], v147 offset:2176
	ds_read_b128 v[78:81], v147 offset:2192
	ds_read_b128 v[82:85], v147 offset:4352
	ds_read_b128 v[86:89], v147 offset:4368
	ds_read_b128 v[90:93], v147 offset:6528
	ds_read_b128 v[94:97], v147 offset:6544
	s_waitcnt lgkmcnt(6)
	v_cvt_pk_bf16_f32 v154, v66, v67
	v_cvt_pk_bf16_f32 v155, v68, v69
	v_cvt_pk_bf16_f32 v156, v70, v71
	v_cvt_pk_bf16_f32 v157, v72, v73
	global_store_dwordx4 v148, v[154:157], s[8:9]
	s_add_u32 s8, s8, 0xf000
	s_addc_u32 s9, s9, 0
	s_waitcnt lgkmcnt(4)
	v_cvt_pk_bf16_f32 v158, v74, v75
	v_cvt_pk_bf16_f32 v159, v76, v77
	v_cvt_pk_bf16_f32 v160, v78, v79
	v_cvt_pk_bf16_f32 v161, v80, v81
	global_store_dwordx4 v148, v[158:161], s[8:9]
	s_add_u32 s8, s8, 0xf000
	s_addc_u32 s9, s9, 0
	s_waitcnt lgkmcnt(2)
	v_cvt_pk_bf16_f32 v162, v82, v83
	v_cvt_pk_bf16_f32 v163, v84, v85
	v_cvt_pk_bf16_f32 v164, v86, v87
	v_cvt_pk_bf16_f32 v165, v88, v89
	global_store_dwordx4 v148, v[162:165], s[8:9]
	s_add_u32 s8, s8, 0xf000
	s_addc_u32 s9, s9, 0
	s_waitcnt lgkmcnt(0)
	v_cvt_pk_bf16_f32 v166, v90, v91
	v_cvt_pk_bf16_f32 v167, v92, v93
	v_cvt_pk_bf16_f32 v168, v94, v95
	v_cvt_pk_bf16_f32 v169, v96, v97
	global_store_dwordx4 v148, v[166:169], s[8:9]
	s_add_u32 s8, s8, 0xf000
	s_addc_u32 s9, s9, 0
	ds_write2_b32 v146, v50, v34 offset0:0 offset1:32
	ds_write2_b32 v146, v51, v35 offset0:68 offset1:100
	ds_write2_b32 v146, v52, v36 offset0:136 offset1:168
	ds_write2_b32 v146, v53, v37 offset0:204 offset1:236
	v_add_u32_e32 v146, 0x880, v146
	ds_write2_b32 v146, v54, v38 offset0:0 offset1:32
	ds_write2_b32 v146, v55, v39 offset0:68 offset1:100
	ds_write2_b32 v146, v56, v40 offset0:136 offset1:168
	ds_write2_b32 v146, v57, v41 offset0:204 offset1:236
	v_add_u32_e32 v146, 0x880, v146
	ds_write2_b32 v146, v58, v42 offset0:0 offset1:32
	ds_write2_b32 v146, v59, v43 offset0:68 offset1:100
	ds_write2_b32 v146, v60, v44 offset0:136 offset1:168
	ds_write2_b32 v146, v61, v45 offset0:204 offset1:236
	v_add_u32_e32 v146, 0x880, v146
	ds_write2_b32 v146, v62, v46 offset0:0 offset1:32
	ds_write2_b32 v146, v63, v47 offset0:68 offset1:100
	ds_write2_b32 v146, v64, v48 offset0:136 offset1:168
	ds_write2_b32 v146, v65, v49 offset0:204 offset1:236
	v_subrev_u32_e32 v146, 0x1980, v146
	ds_read_b128 v[34:37], v147
	ds_read_b128 v[38:41], v147 offset:16
	ds_read_b128 v[42:45], v147 offset:2176
	ds_read_b128 v[46:49], v147 offset:2192
	ds_read_b128 v[50:53], v147 offset:4352
	ds_read_b128 v[54:57], v147 offset:4368
	ds_read_b128 v[58:61], v147 offset:6528
	ds_read_b128 v[62:65], v147 offset:6544
	s_waitcnt lgkmcnt(6)
	v_cvt_pk_bf16_f32 v154, v34, v35
	v_cvt_pk_bf16_f32 v155, v36, v37
	v_cvt_pk_bf16_f32 v156, v38, v39
	v_cvt_pk_bf16_f32 v157, v40, v41
	global_store_dwordx4 v148, v[154:157], s[8:9]
	s_add_u32 s8, s8, 0xf000
	s_addc_u32 s9, s9, 0
	s_waitcnt lgkmcnt(4)
	v_cvt_pk_bf16_f32 v158, v42, v43
	v_cvt_pk_bf16_f32 v159, v44, v45
	v_cvt_pk_bf16_f32 v160, v46, v47
	v_cvt_pk_bf16_f32 v161, v48, v49
	global_store_dwordx4 v148, v[158:161], s[8:9]
	s_add_u32 s8, s8, 0xf000
	s_addc_u32 s9, s9, 0
	s_waitcnt lgkmcnt(2)
	v_cvt_pk_bf16_f32 v162, v50, v51
	v_cvt_pk_bf16_f32 v163, v52, v53
	v_cvt_pk_bf16_f32 v164, v54, v55
	v_cvt_pk_bf16_f32 v165, v56, v57
	global_store_dwordx4 v148, v[162:165], s[8:9]
	s_add_u32 s8, s8, 0xf000
	s_addc_u32 s9, s9, 0
	s_waitcnt lgkmcnt(0)
	v_cvt_pk_bf16_f32 v166, v58, v59
	v_cvt_pk_bf16_f32 v167, v60, v61
	v_cvt_pk_bf16_f32 v168, v62, v63
	v_cvt_pk_bf16_f32 v169, v64, v65
	global_store_dwordx4 v148, v[166:169], s[8:9]
	s_add_u32 s8, s8, 0xf000
	s_addc_u32 s9, s9, 0
	ds_write2_b32 v146, v18, v2 offset0:0 offset1:32
	ds_write2_b32 v146, v19, v3 offset0:68 offset1:100
	ds_write2_b32 v146, v20, v4 offset0:136 offset1:168
	ds_write2_b32 v146, v21, v5 offset0:204 offset1:236
	v_add_u32_e32 v146, 0x880, v146
	ds_write2_b32 v146, v22, v6 offset0:0 offset1:32
	ds_write2_b32 v146, v23, v7 offset0:68 offset1:100
	ds_write2_b32 v146, v24, v8 offset0:136 offset1:168
	ds_write2_b32 v146, v25, v9 offset0:204 offset1:236
	v_add_u32_e32 v146, 0x880, v146
	ds_write2_b32 v146, v26, v10 offset0:0 offset1:32
	ds_write2_b32 v146, v27, v11 offset0:68 offset1:100
	ds_write2_b32 v146, v28, v12 offset0:136 offset1:168
	ds_write2_b32 v146, v29, v13 offset0:204 offset1:236
	v_add_u32_e32 v146, 0x880, v146
	ds_write2_b32 v146, v30, v14 offset0:0 offset1:32
	ds_write2_b32 v146, v31, v15 offset0:68 offset1:100
	ds_write2_b32 v146, v32, v16 offset0:136 offset1:168
	ds_write2_b32 v146, v33, v17 offset0:204 offset1:236
	v_subrev_u32_e32 v146, 0x1980, v146
	ds_read_b128 v[2:5], v147
	ds_read_b128 v[6:9], v147 offset:16
	ds_read_b128 v[10:13], v147 offset:2176
	ds_read_b128 v[14:17], v147 offset:2192
	ds_read_b128 v[18:21], v147 offset:4352
	ds_read_b128 v[22:25], v147 offset:4368
	ds_read_b128 v[26:29], v147 offset:6528
	ds_read_b128 v[30:33], v147 offset:6544
	s_waitcnt lgkmcnt(0)
	s_barrier
	v_cvt_pk_bf16_f32 v154, v2, v3
	v_cvt_pk_bf16_f32 v155, v4, v5
	v_cvt_pk_bf16_f32 v156, v6, v7
	v_cvt_pk_bf16_f32 v157, v8, v9
	global_store_dwordx4 v148, v[154:157], s[8:9]
	s_add_u32 s8, s8, 0xf000
	s_addc_u32 s9, s9, 0
	v_cvt_pk_bf16_f32 v158, v10, v11
	v_cvt_pk_bf16_f32 v159, v12, v13
	v_cvt_pk_bf16_f32 v160, v14, v15
	v_cvt_pk_bf16_f32 v161, v16, v17
	global_store_dwordx4 v148, v[158:161], s[8:9]
	s_add_u32 s8, s8, 0xf000
	s_addc_u32 s9, s9, 0
	v_cvt_pk_bf16_f32 v162, v18, v19
	v_cvt_pk_bf16_f32 v163, v20, v21
	v_cvt_pk_bf16_f32 v164, v22, v23
	v_cvt_pk_bf16_f32 v165, v24, v25
	global_store_dwordx4 v148, v[162:165], s[8:9]
	s_add_u32 s8, s8, 0xf000
	s_addc_u32 s9, s9, 0
	v_cvt_pk_bf16_f32 v166, v26, v27
	v_cvt_pk_bf16_f32 v167, v28, v29
	v_cvt_pk_bf16_f32 v168, v30, v31
	v_cvt_pk_bf16_f32 v169, v32, v33
	global_store_dwordx4 v148, v[166:169], s[8:9]
	s_add_u32 s8, s8, 0xf000
	s_addc_u32 s9, s9, 0
	s_add_i32 s70, s70, s10
	s_cmp_lt_i32 s70, s71
	s_cbranch_scc0 .LBB0_209
	s_branch .LBB0_215
.Lmy_g0e_gate:
	ds_write2_b32 v146, v114, v98 offset0:0 offset1:32
	ds_write2_b32 v146, v115, v99 offset0:68 offset1:100
	ds_write2_b32 v146, v116, v100 offset0:136 offset1:168
	ds_write2_b32 v146, v117, v101 offset0:204 offset1:236
	v_add_u32_e32 v146, 0x880, v146
	ds_write2_b32 v146, v118, v102 offset0:0 offset1:32
	ds_write2_b32 v146, v119, v103 offset0:68 offset1:100
	ds_write2_b32 v146, v120, v104 offset0:136 offset1:168
	ds_write2_b32 v146, v121, v105 offset0:204 offset1:236
	v_add_u32_e32 v146, 0x880, v146
	ds_write2_b32 v146, v122, v106 offset0:0 offset1:32
	ds_write2_b32 v146, v123, v107 offset0:68 offset1:100
	ds_write2_b32 v146, v124, v108 offset0:136 offset1:168
	ds_write2_b32 v146, v125, v109 offset0:204 offset1:236
	v_add_u32_e32 v146, 0x880, v146
	ds_write2_b32 v146, v126, v110 offset0:0 offset1:32
	ds_write2_b32 v146, v127, v111 offset0:68 offset1:100
	ds_write2_b32 v146, v128, v112 offset0:136 offset1:168
	ds_write2_b32 v146, v129, v113 offset0:204 offset1:236
	v_subrev_u32_e32 v146, 0x1980, v146
	ds_read_b128 v[98:101], v147
	ds_read_b128 v[102:105], v147 offset:16
	ds_read_b128 v[106:109], v147 offset:2176
	ds_read_b128 v[110:113], v147 offset:2192
	ds_read_b128 v[114:117], v147 offset:4352
	ds_read_b128 v[118:121], v147 offset:4368
	ds_read_b128 v[122:125], v147 offset:6528
	ds_read_b128 v[126:129], v147 offset:6544
	s_waitcnt lgkmcnt(6)
	v_mul_f32_e32 v170, 0xbfb8aa3b, v98
	v_mul_f32_e32 v171, 0xbfb8aa3b, v99
	v_mul_f32_e32 v172, 0xbfb8aa3b, v100
	v_mul_f32_e32 v173, 0xbfb8aa3b, v101
	v_exp_f32_e32 v170, v170
	v_exp_f32_e32 v171, v171
	v_exp_f32_e32 v172, v172
	v_exp_f32_e32 v173, v173
	v_add_f32_e32 v170, 1.0, v170
	v_add_f32_e32 v171, 1.0, v171
	v_add_f32_e32 v172, 1.0, v172
	v_add_f32_e32 v173, 1.0, v173
	v_rcp_f32_e32 v170, v170
	v_rcp_f32_e32 v171, v171
	v_rcp_f32_e32 v172, v172
	v_rcp_f32_e32 v173, v173
	s_nop 0
	v_mul_f32_e32 v98, v98, v170
	v_mul_f32_e32 v99, v99, v171
	v_mul_f32_e32 v100, v100, v172
	v_mul_f32_e32 v101, v101, v173
	v_cvt_pk_bf16_f32 v154, v98, v99
	v_cvt_pk_bf16_f32 v155, v100, v101
	v_mul_f32_e32 v170, 0xbfb8aa3b, v102
	v_mul_f32_e32 v171, 0xbfb8aa3b, v103
	v_mul_f32_e32 v172, 0xbfb8aa3b, v104
	v_mul_f32_e32 v173, 0xbfb8aa3b, v105
	v_exp_f32_e32 v170, v170
	v_exp_f32_e32 v171, v171
	v_exp_f32_e32 v172, v172
	v_exp_f32_e32 v173, v173
	v_add_f32_e32 v170, 1.0, v170
	v_add_f32_e32 v171, 1.0, v171
	v_add_f32_e32 v172, 1.0, v172
	v_add_f32_e32 v173, 1.0, v173
	v_rcp_f32_e32 v170, v170
	v_rcp_f32_e32 v171, v171
	v_rcp_f32_e32 v172, v172
	v_rcp_f32_e32 v173, v173
	s_nop 0
	v_mul_f32_e32 v102, v102, v170
	v_mul_f32_e32 v103, v103, v171
	v_mul_f32_e32 v104, v104, v172
	v_mul_f32_e32 v105, v105, v173
	v_cvt_pk_bf16_f32 v156, v102, v103
	v_cvt_pk_bf16_f32 v157, v104, v105
	global_store_dwordx4 v148, v[154:157], s[8:9]
	s_add_u32 s8, s8, 0xf000
	s_addc_u32 s9, s9, 0
	s_waitcnt lgkmcnt(4)
	v_mul_f32_e32 v170, 0xbfb8aa3b, v106
	v_mul_f32_e32 v171, 0xbfb8aa3b, v107
	v_mul_f32_e32 v172, 0xbfb8aa3b, v108
	v_mul_f32_e32 v173, 0xbfb8aa3b, v109
	v_exp_f32_e32 v170, v170
	v_exp_f32_e32 v171, v171
	v_exp_f32_e32 v172, v172
	v_exp_f32_e32 v173, v173
	v_add_f32_e32 v170, 1.0, v170
	v_add_f32_e32 v171, 1.0, v171
	v_add_f32_e32 v172, 1.0, v172
	v_add_f32_e32 v173, 1.0, v173
	v_rcp_f32_e32 v170, v170
	v_rcp_f32_e32 v171, v171
	v_rcp_f32_e32 v172, v172
	v_rcp_f32_e32 v173, v173
	s_nop 0
	v_mul_f32_e32 v106, v106, v170
	v_mul_f32_e32 v107, v107, v171
	v_mul_f32_e32 v108, v108, v172
	v_mul_f32_e32 v109, v109, v173
	v_cvt_pk_bf16_f32 v158, v106, v107
	v_cvt_pk_bf16_f32 v159, v108, v109
	v_mul_f32_e32 v170, 0xbfb8aa3b, v110
	v_mul_f32_e32 v171, 0xbfb8aa3b, v111
	v_mul_f32_e32 v172, 0xbfb8aa3b, v112
	v_mul_f32_e32 v173, 0xbfb8aa3b, v113
	v_exp_f32_e32 v170, v170
	v_exp_f32_e32 v171, v171
	v_exp_f32_e32 v172, v172
	v_exp_f32_e32 v173, v173
	v_add_f32_e32 v170, 1.0, v170
	v_add_f32_e32 v171, 1.0, v171
	v_add_f32_e32 v172, 1.0, v172
	v_add_f32_e32 v173, 1.0, v173
	v_rcp_f32_e32 v170, v170
	v_rcp_f32_e32 v171, v171
	v_rcp_f32_e32 v172, v172
	v_rcp_f32_e32 v173, v173
	s_nop 0
	v_mul_f32_e32 v110, v110, v170
	v_mul_f32_e32 v111, v111, v171
	v_mul_f32_e32 v112, v112, v172
	v_mul_f32_e32 v113, v113, v173
	v_cvt_pk_bf16_f32 v160, v110, v111
	v_cvt_pk_bf16_f32 v161, v112, v113
	global_store_dwordx4 v148, v[158:161], s[8:9]
	s_add_u32 s8, s8, 0xf000
	s_addc_u32 s9, s9, 0
	s_waitcnt lgkmcnt(2)
	v_mul_f32_e32 v170, 0xbfb8aa3b, v114
	v_mul_f32_e32 v171, 0xbfb8aa3b, v115
	v_mul_f32_e32 v172, 0xbfb8aa3b, v116
	v_mul_f32_e32 v173, 0xbfb8aa3b, v117
	v_exp_f32_e32 v170, v170
	v_exp_f32_e32 v171, v171
	v_exp_f32_e32 v172, v172
	v_exp_f32_e32 v173, v173
	v_add_f32_e32 v170, 1.0, v170
	v_add_f32_e32 v171, 1.0, v171
	v_add_f32_e32 v172, 1.0, v172
	v_add_f32_e32 v173, 1.0, v173
	v_rcp_f32_e32 v170, v170
	v_rcp_f32_e32 v171, v171
	v_rcp_f32_e32 v172, v172
	v_rcp_f32_e32 v173, v173
	s_nop 0
	v_mul_f32_e32 v114, v114, v170
	v_mul_f32_e32 v115, v115, v171
	v_mul_f32_e32 v116, v116, v172
	v_mul_f32_e32 v117, v117, v173
	v_cvt_pk_bf16_f32 v162, v114, v115
	v_cvt_pk_bf16_f32 v163, v116, v117
	v_mul_f32_e32 v170, 0xbfb8aa3b, v118
	v_mul_f32_e32 v171, 0xbfb8aa3b, v119
	v_mul_f32_e32 v172, 0xbfb8aa3b, v120
	v_mul_f32_e32 v173, 0xbfb8aa3b, v121
	v_exp_f32_e32 v170, v170
	v_exp_f32_e32 v171, v171
	v_exp_f32_e32 v172, v172
	v_exp_f32_e32 v173, v173
	v_add_f32_e32 v170, 1.0, v170
	v_add_f32_e32 v171, 1.0, v171
	v_add_f32_e32 v172, 1.0, v172
	v_add_f32_e32 v173, 1.0, v173
	v_rcp_f32_e32 v170, v170
	v_rcp_f32_e32 v171, v171
	v_rcp_f32_e32 v172, v172
	v_rcp_f32_e32 v173, v173
	s_nop 0
	v_mul_f32_e32 v118, v118, v170
	v_mul_f32_e32 v119, v119, v171
	v_mul_f32_e32 v120, v120, v172
	v_mul_f32_e32 v121, v121, v173
	v_cvt_pk_bf16_f32 v164, v118, v119
	v_cvt_pk_bf16_f32 v165, v120, v121
	global_store_dwordx4 v148, v[162:165], s[8:9]
	s_add_u32 s8, s8, 0xf000
	s_addc_u32 s9, s9, 0
	s_waitcnt lgkmcnt(0)
	v_mul_f32_e32 v170, 0xbfb8aa3b, v122
	v_mul_f32_e32 v171, 0xbfb8aa3b, v123
	v_mul_f32_e32 v172, 0xbfb8aa3b, v124
	v_mul_f32_e32 v173, 0xbfb8aa3b, v125
	v_exp_f32_e32 v170, v170
	v_exp_f32_e32 v171, v171
	v_exp_f32_e32 v172, v172
	v_exp_f32_e32 v173, v173
	v_add_f32_e32 v170, 1.0, v170
	v_add_f32_e32 v171, 1.0, v171
	v_add_f32_e32 v172, 1.0, v172
	v_add_f32_e32 v173, 1.0, v173
	v_rcp_f32_e32 v170, v170
	v_rcp_f32_e32 v171, v171
	v_rcp_f32_e32 v172, v172
	v_rcp_f32_e32 v173, v173
	s_nop 0
	v_mul_f32_e32 v122, v122, v170
	v_mul_f32_e32 v123, v123, v171
	v_mul_f32_e32 v124, v124, v172
	v_mul_f32_e32 v125, v125, v173
	v_cvt_pk_bf16_f32 v166, v122, v123
	v_cvt_pk_bf16_f32 v167, v124, v125
	v_mul_f32_e32 v170, 0xbfb8aa3b, v126
	v_mul_f32_e32 v171, 0xbfb8aa3b, v127
	v_mul_f32_e32 v172, 0xbfb8aa3b, v128
	v_mul_f32_e32 v173, 0xbfb8aa3b, v129
	v_exp_f32_e32 v170, v170
	v_exp_f32_e32 v171, v171
	v_exp_f32_e32 v172, v172
	v_exp_f32_e32 v173, v173
	v_add_f32_e32 v170, 1.0, v170
	v_add_f32_e32 v171, 1.0, v171
	v_add_f32_e32 v172, 1.0, v172
	v_add_f32_e32 v173, 1.0, v173
	v_rcp_f32_e32 v170, v170
	v_rcp_f32_e32 v171, v171
	v_rcp_f32_e32 v172, v172
	v_rcp_f32_e32 v173, v173
	s_nop 0
	v_mul_f32_e32 v126, v126, v170
	v_mul_f32_e32 v127, v127, v171
	v_mul_f32_e32 v128, v128, v172
	v_mul_f32_e32 v129, v129, v173
	v_cvt_pk_bf16_f32 v168, v126, v127
	v_cvt_pk_bf16_f32 v169, v128, v129
	global_store_dwordx4 v148, v[166:169], s[8:9]
	s_add_u32 s8, s8, 0xf000
	s_addc_u32 s9, s9, 0
	ds_write2_b32 v146, v82, v66 offset0:0 offset1:32
	ds_write2_b32 v146, v83, v67 offset0:68 offset1:100
	ds_write2_b32 v146, v84, v68 offset0:136 offset1:168
	ds_write2_b32 v146, v85, v69 offset0:204 offset1:236
	v_add_u32_e32 v146, 0x880, v146
	ds_write2_b32 v146, v86, v70 offset0:0 offset1:32
	ds_write2_b32 v146, v87, v71 offset0:68 offset1:100
	ds_write2_b32 v146, v88, v72 offset0:136 offset1:168
	ds_write2_b32 v146, v89, v73 offset0:204 offset1:236
	v_add_u32_e32 v146, 0x880, v146
	ds_write2_b32 v146, v90, v74 offset0:0 offset1:32
	ds_write2_b32 v146, v91, v75 offset0:68 offset1:100
	ds_write2_b32 v146, v92, v76 offset0:136 offset1:168
	ds_write2_b32 v146, v93, v77 offset0:204 offset1:236
	v_add_u32_e32 v146, 0x880, v146
	ds_write2_b32 v146, v94, v78 offset0:0 offset1:32
	ds_write2_b32 v146, v95, v79 offset0:68 offset1:100
	ds_write2_b32 v146, v96, v80 offset0:136 offset1:168
	ds_write2_b32 v146, v97, v81 offset0:204 offset1:236
	v_subrev_u32_e32 v146, 0x1980, v146
	ds_read_b128 v[66:69], v147
	ds_read_b128 v[70:73], v147 offset:16
	ds_read_b128 v[74:77], v147 offset:2176
	ds_read_b128 v[78:81], v147 offset:2192
	ds_read_b128 v[82:85], v147 offset:4352
	ds_read_b128 v[86:89], v147 offset:4368
	ds_read_b128 v[90:93], v147 offset:6528
	ds_read_b128 v[94:97], v147 offset:6544
	s_waitcnt lgkmcnt(6)
	v_mul_f32_e32 v170, 0xbfb8aa3b, v66
	v_mul_f32_e32 v171, 0xbfb8aa3b, v67
	v_mul_f32_e32 v172, 0xbfb8aa3b, v68
	v_mul_f32_e32 v173, 0xbfb8aa3b, v69
	v_exp_f32_e32 v170, v170
	v_exp_f32_e32 v171, v171
	v_exp_f32_e32 v172, v172
	v_exp_f32_e32 v173, v173
	v_add_f32_e32 v170, 1.0, v170
	v_add_f32_e32 v171, 1.0, v171
	v_add_f32_e32 v172, 1.0, v172
	v_add_f32_e32 v173, 1.0, v173
	v_rcp_f32_e32 v170, v170
	v_rcp_f32_e32 v171, v171
	v_rcp_f32_e32 v172, v172
	v_rcp_f32_e32 v173, v173
	s_nop 0
	v_mul_f32_e32 v66, v66, v170
	v_mul_f32_e32 v67, v67, v171
	v_mul_f32_e32 v68, v68, v172
	v_mul_f32_e32 v69, v69, v173
	v_cvt_pk_bf16_f32 v154, v66, v67
	v_cvt_pk_bf16_f32 v155, v68, v69
	v_mul_f32_e32 v170, 0xbfb8aa3b, v70
	v_mul_f32_e32 v171, 0xbfb8aa3b, v71
	v_mul_f32_e32 v172, 0xbfb8aa3b, v72
	v_mul_f32_e32 v173, 0xbfb8aa3b, v73
	v_exp_f32_e32 v170, v170
	v_exp_f32_e32 v171, v171
	v_exp_f32_e32 v172, v172
	v_exp_f32_e32 v173, v173
	v_add_f32_e32 v170, 1.0, v170
	v_add_f32_e32 v171, 1.0, v171
	v_add_f32_e32 v172, 1.0, v172
	v_add_f32_e32 v173, 1.0, v173
	v_rcp_f32_e32 v170, v170
	v_rcp_f32_e32 v171, v171
	v_rcp_f32_e32 v172, v172
	v_rcp_f32_e32 v173, v173
	s_nop 0
	v_mul_f32_e32 v70, v70, v170
	v_mul_f32_e32 v71, v71, v171
	v_mul_f32_e32 v72, v72, v172
	v_mul_f32_e32 v73, v73, v173
	v_cvt_pk_bf16_f32 v156, v70, v71
	v_cvt_pk_bf16_f32 v157, v72, v73
	global_store_dwordx4 v148, v[154:157], s[8:9]
	s_add_u32 s8, s8, 0xf000
	s_addc_u32 s9, s9, 0
	s_waitcnt lgkmcnt(4)
	v_mul_f32_e32 v170, 0xbfb8aa3b, v74
	v_mul_f32_e32 v171, 0xbfb8aa3b, v75
	v_mul_f32_e32 v172, 0xbfb8aa3b, v76
	v_mul_f32_e32 v173, 0xbfb8aa3b, v77
	v_exp_f32_e32 v170, v170
	v_exp_f32_e32 v171, v171
	v_exp_f32_e32 v172, v172
	v_exp_f32_e32 v173, v173
	v_add_f32_e32 v170, 1.0, v170
	v_add_f32_e32 v171, 1.0, v171
	v_add_f32_e32 v172, 1.0, v172
	v_add_f32_e32 v173, 1.0, v173
	v_rcp_f32_e32 v170, v170
	v_rcp_f32_e32 v171, v171
	v_rcp_f32_e32 v172, v172
	v_rcp_f32_e32 v173, v173
	s_nop 0
	v_mul_f32_e32 v74, v74, v170
	v_mul_f32_e32 v75, v75, v171
	v_mul_f32_e32 v76, v76, v172
	v_mul_f32_e32 v77, v77, v173
	v_cvt_pk_bf16_f32 v158, v74, v75
	v_cvt_pk_bf16_f32 v159, v76, v77
	v_mul_f32_e32 v170, 0xbfb8aa3b, v78
	v_mul_f32_e32 v171, 0xbfb8aa3b, v79
	v_mul_f32_e32 v172, 0xbfb8aa3b, v80
	v_mul_f32_e32 v173, 0xbfb8aa3b, v81
	v_exp_f32_e32 v170, v170
	v_exp_f32_e32 v171, v171
	v_exp_f32_e32 v172, v172
	v_exp_f32_e32 v173, v173
	v_add_f32_e32 v170, 1.0, v170
	v_add_f32_e32 v171, 1.0, v171
	v_add_f32_e32 v172, 1.0, v172
	v_add_f32_e32 v173, 1.0, v173
	v_rcp_f32_e32 v170, v170
	v_rcp_f32_e32 v171, v171
	v_rcp_f32_e32 v172, v172
	v_rcp_f32_e32 v173, v173
	s_nop 0
	v_mul_f32_e32 v78, v78, v170
	v_mul_f32_e32 v79, v79, v171
	v_mul_f32_e32 v80, v80, v172
	v_mul_f32_e32 v81, v81, v173
	v_cvt_pk_bf16_f32 v160, v78, v79
	v_cvt_pk_bf16_f32 v161, v80, v81
	global_store_dwordx4 v148, v[158:161], s[8:9]
	s_add_u32 s8, s8, 0xf000
	s_addc_u32 s9, s9, 0
	s_waitcnt lgkmcnt(2)
	v_mul_f32_e32 v170, 0xbfb8aa3b, v82
	v_mul_f32_e32 v171, 0xbfb8aa3b, v83
	v_mul_f32_e32 v172, 0xbfb8aa3b, v84
	v_mul_f32_e32 v173, 0xbfb8aa3b, v85
	v_exp_f32_e32 v170, v170
	v_exp_f32_e32 v171, v171
	v_exp_f32_e32 v172, v172
	v_exp_f32_e32 v173, v173
	v_add_f32_e32 v170, 1.0, v170
	v_add_f32_e32 v171, 1.0, v171
	v_add_f32_e32 v172, 1.0, v172
	v_add_f32_e32 v173, 1.0, v173
	v_rcp_f32_e32 v170, v170
	v_rcp_f32_e32 v171, v171
	v_rcp_f32_e32 v172, v172
	v_rcp_f32_e32 v173, v173
	s_nop 0
	v_mul_f32_e32 v82, v82, v170
	v_mul_f32_e32 v83, v83, v171
	v_mul_f32_e32 v84, v84, v172
	v_mul_f32_e32 v85, v85, v173
	v_cvt_pk_bf16_f32 v162, v82, v83
	v_cvt_pk_bf16_f32 v163, v84, v85
	v_mul_f32_e32 v170, 0xbfb8aa3b, v86
	v_mul_f32_e32 v171, 0xbfb8aa3b, v87
	v_mul_f32_e32 v172, 0xbfb8aa3b, v88
	v_mul_f32_e32 v173, 0xbfb8aa3b, v89
	v_exp_f32_e32 v170, v170
	v_exp_f32_e32 v171, v171
	v_exp_f32_e32 v172, v172
	v_exp_f32_e32 v173, v173
	v_add_f32_e32 v170, 1.0, v170
	v_add_f32_e32 v171, 1.0, v171
	v_add_f32_e32 v172, 1.0, v172
	v_add_f32_e32 v173, 1.0, v173
	v_rcp_f32_e32 v170, v170
	v_rcp_f32_e32 v171, v171
	v_rcp_f32_e32 v172, v172
	v_rcp_f32_e32 v173, v173
	s_nop 0
	v_mul_f32_e32 v86, v86, v170
	v_mul_f32_e32 v87, v87, v171
	v_mul_f32_e32 v88, v88, v172
	v_mul_f32_e32 v89, v89, v173
	v_cvt_pk_bf16_f32 v164, v86, v87
	v_cvt_pk_bf16_f32 v165, v88, v89
	global_store_dwordx4 v148, v[162:165], s[8:9]
	s_add_u32 s8, s8, 0xf000
	s_addc_u32 s9, s9, 0
	s_waitcnt lgkmcnt(0)
	v_mul_f32_e32 v170, 0xbfb8aa3b, v90
	v_mul_f32_e32 v171, 0xbfb8aa3b, v91
	v_mul_f32_e32 v172, 0xbfb8aa3b, v92
	v_mul_f32_e32 v173, 0xbfb8aa3b, v93
	v_exp_f32_e32 v170, v170
	v_exp_f32_e32 v171, v171
	v_exp_f32_e32 v172, v172
	v_exp_f32_e32 v173, v173
	v_add_f32_e32 v170, 1.0, v170
	v_add_f32_e32 v171, 1.0, v171
	v_add_f32_e32 v172, 1.0, v172
	v_add_f32_e32 v173, 1.0, v173
	v_rcp_f32_e32 v170, v170
	v_rcp_f32_e32 v171, v171
	v_rcp_f32_e32 v172, v172
	v_rcp_f32_e32 v173, v173
	s_nop 0
	v_mul_f32_e32 v90, v90, v170
	v_mul_f32_e32 v91, v91, v171
	v_mul_f32_e32 v92, v92, v172
	v_mul_f32_e32 v93, v93, v173
	v_cvt_pk_bf16_f32 v166, v90, v91
	v_cvt_pk_bf16_f32 v167, v92, v93
	v_mul_f32_e32 v170, 0xbfb8aa3b, v94
	v_mul_f32_e32 v171, 0xbfb8aa3b, v95
	v_mul_f32_e32 v172, 0xbfb8aa3b, v96
	v_mul_f32_e32 v173, 0xbfb8aa3b, v97
	v_exp_f32_e32 v170, v170
	v_exp_f32_e32 v171, v171
	v_exp_f32_e32 v172, v172
	v_exp_f32_e32 v173, v173
	v_add_f32_e32 v170, 1.0, v170
	v_add_f32_e32 v171, 1.0, v171
	v_add_f32_e32 v172, 1.0, v172
	v_add_f32_e32 v173, 1.0, v173
	v_rcp_f32_e32 v170, v170
	v_rcp_f32_e32 v171, v171
	v_rcp_f32_e32 v172, v172
	v_rcp_f32_e32 v173, v173
	s_nop 0
	v_mul_f32_e32 v94, v94, v170
	v_mul_f32_e32 v95, v95, v171
	v_mul_f32_e32 v96, v96, v172
	v_mul_f32_e32 v97, v97, v173
	v_cvt_pk_bf16_f32 v168, v94, v95
	v_cvt_pk_bf16_f32 v169, v96, v97
	global_store_dwordx4 v148, v[166:169], s[8:9]
	s_add_u32 s8, s8, 0xf000
	s_addc_u32 s9, s9, 0
	ds_write2_b32 v146, v50, v34 offset0:0 offset1:32
	ds_write2_b32 v146, v51, v35 offset0:68 offset1:100
	ds_write2_b32 v146, v52, v36 offset0:136 offset1:168
	ds_write2_b32 v146, v53, v37 offset0:204 offset1:236
	v_add_u32_e32 v146, 0x880, v146
	ds_write2_b32 v146, v54, v38 offset0:0 offset1:32
	ds_write2_b32 v146, v55, v39 offset0:68 offset1:100
	ds_write2_b32 v146, v56, v40 offset0:136 offset1:168
	ds_write2_b32 v146, v57, v41 offset0:204 offset1:236
	v_add_u32_e32 v146, 0x880, v146
	ds_write2_b32 v146, v58, v42 offset0:0 offset1:32
	ds_write2_b32 v146, v59, v43 offset0:68 offset1:100
	ds_write2_b32 v146, v60, v44 offset0:136 offset1:168
	ds_write2_b32 v146, v61, v45 offset0:204 offset1:236
	v_add_u32_e32 v146, 0x880, v146
	ds_write2_b32 v146, v62, v46 offset0:0 offset1:32
	ds_write2_b32 v146, v63, v47 offset0:68 offset1:100
	ds_write2_b32 v146, v64, v48 offset0:136 offset1:168
	ds_write2_b32 v146, v65, v49 offset0:204 offset1:236
	v_subrev_u32_e32 v146, 0x1980, v146
	ds_read_b128 v[34:37], v147
	ds_read_b128 v[38:41], v147 offset:16
	ds_read_b128 v[42:45], v147 offset:2176
	ds_read_b128 v[46:49], v147 offset:2192
	ds_read_b128 v[50:53], v147 offset:4352
	ds_read_b128 v[54:57], v147 offset:4368
	ds_read_b128 v[58:61], v147 offset:6528
	ds_read_b128 v[62:65], v147 offset:6544
	s_waitcnt lgkmcnt(6)
	v_mul_f32_e32 v170, 0xbfb8aa3b, v34
	v_mul_f32_e32 v171, 0xbfb8aa3b, v35
	v_mul_f32_e32 v172, 0xbfb8aa3b, v36
	v_mul_f32_e32 v173, 0xbfb8aa3b, v37
	v_exp_f32_e32 v170, v170
	v_exp_f32_e32 v171, v171
	v_exp_f32_e32 v172, v172
	v_exp_f32_e32 v173, v173
	v_add_f32_e32 v170, 1.0, v170
	v_add_f32_e32 v171, 1.0, v171
	v_add_f32_e32 v172, 1.0, v172
	v_add_f32_e32 v173, 1.0, v173
	v_rcp_f32_e32 v170, v170
	v_rcp_f32_e32 v171, v171
	v_rcp_f32_e32 v172, v172
	v_rcp_f32_e32 v173, v173
	s_nop 0
	v_mul_f32_e32 v34, v34, v170
	v_mul_f32_e32 v35, v35, v171
	v_mul_f32_e32 v36, v36, v172
	v_mul_f32_e32 v37, v37, v173
	v_cvt_pk_bf16_f32 v154, v34, v35
	v_cvt_pk_bf16_f32 v155, v36, v37
	v_mul_f32_e32 v170, 0xbfb8aa3b, v38
	v_mul_f32_e32 v171, 0xbfb8aa3b, v39
	v_mul_f32_e32 v172, 0xbfb8aa3b, v40
	v_mul_f32_e32 v173, 0xbfb8aa3b, v41
	v_exp_f32_e32 v170, v170
	v_exp_f32_e32 v171, v171
	v_exp_f32_e32 v172, v172
	v_exp_f32_e32 v173, v173
	v_add_f32_e32 v170, 1.0, v170
	v_add_f32_e32 v171, 1.0, v171
	v_add_f32_e32 v172, 1.0, v172
	v_add_f32_e32 v173, 1.0, v173
	v_rcp_f32_e32 v170, v170
	v_rcp_f32_e32 v171, v171
	v_rcp_f32_e32 v172, v172
	v_rcp_f32_e32 v173, v173
	s_nop 0
	v_mul_f32_e32 v38, v38, v170
	v_mul_f32_e32 v39, v39, v171
	v_mul_f32_e32 v40, v40, v172
	v_mul_f32_e32 v41, v41, v173
	v_cvt_pk_bf16_f32 v156, v38, v39
	v_cvt_pk_bf16_f32 v157, v40, v41
	global_store_dwordx4 v148, v[154:157], s[8:9]
	s_add_u32 s8, s8, 0xf000
	s_addc_u32 s9, s9, 0
	s_waitcnt lgkmcnt(4)
	v_mul_f32_e32 v170, 0xbfb8aa3b, v42
	v_mul_f32_e32 v171, 0xbfb8aa3b, v43
	v_mul_f32_e32 v172, 0xbfb8aa3b, v44
	v_mul_f32_e32 v173, 0xbfb8aa3b, v45
	v_exp_f32_e32 v170, v170
	v_exp_f32_e32 v171, v171
	v_exp_f32_e32 v172, v172
	v_exp_f32_e32 v173, v173
	v_add_f32_e32 v170, 1.0, v170
	v_add_f32_e32 v171, 1.0, v171
	v_add_f32_e32 v172, 1.0, v172
	v_add_f32_e32 v173, 1.0, v173
	v_rcp_f32_e32 v170, v170
	v_rcp_f32_e32 v171, v171
	v_rcp_f32_e32 v172, v172
	v_rcp_f32_e32 v173, v173
	s_nop 0
	v_mul_f32_e32 v42, v42, v170
	v_mul_f32_e32 v43, v43, v171
	v_mul_f32_e32 v44, v44, v172
	v_mul_f32_e32 v45, v45, v173
	v_cvt_pk_bf16_f32 v158, v42, v43
	v_cvt_pk_bf16_f32 v159, v44, v45
	v_mul_f32_e32 v170, 0xbfb8aa3b, v46
	v_mul_f32_e32 v171, 0xbfb8aa3b, v47
	v_mul_f32_e32 v172, 0xbfb8aa3b, v48
	v_mul_f32_e32 v173, 0xbfb8aa3b, v49
	v_exp_f32_e32 v170, v170
	v_exp_f32_e32 v171, v171
	v_exp_f32_e32 v172, v172
	v_exp_f32_e32 v173, v173
	v_add_f32_e32 v170, 1.0, v170
	v_add_f32_e32 v171, 1.0, v171
	v_add_f32_e32 v172, 1.0, v172
	v_add_f32_e32 v173, 1.0, v173
	v_rcp_f32_e32 v170, v170
	v_rcp_f32_e32 v171, v171
	v_rcp_f32_e32 v172, v172
	v_rcp_f32_e32 v173, v173
	s_nop 0
	v_mul_f32_e32 v46, v46, v170
	v_mul_f32_e32 v47, v47, v171
	v_mul_f32_e32 v48, v48, v172
	v_mul_f32_e32 v49, v49, v173
	v_cvt_pk_bf16_f32 v160, v46, v47
	v_cvt_pk_bf16_f32 v161, v48, v49
	global_store_dwordx4 v148, v[158:161], s[8:9]
	s_add_u32 s8, s8, 0xf000
	s_addc_u32 s9, s9, 0
	s_waitcnt lgkmcnt(2)
	v_mul_f32_e32 v170, 0xbfb8aa3b, v50
	v_mul_f32_e32 v171, 0xbfb8aa3b, v51
	v_mul_f32_e32 v172, 0xbfb8aa3b, v52
	v_mul_f32_e32 v173, 0xbfb8aa3b, v53
	v_exp_f32_e32 v170, v170
	v_exp_f32_e32 v171, v171
	v_exp_f32_e32 v172, v172
	v_exp_f32_e32 v173, v173
	v_add_f32_e32 v170, 1.0, v170
	v_add_f32_e32 v171, 1.0, v171
	v_add_f32_e32 v172, 1.0, v172
	v_add_f32_e32 v173, 1.0, v173
	v_rcp_f32_e32 v170, v170
	v_rcp_f32_e32 v171, v171
	v_rcp_f32_e32 v172, v172
	v_rcp_f32_e32 v173, v173
	s_nop 0
	v_mul_f32_e32 v50, v50, v170
	v_mul_f32_e32 v51, v51, v171
	v_mul_f32_e32 v52, v52, v172
	v_mul_f32_e32 v53, v53, v173
	v_cvt_pk_bf16_f32 v162, v50, v51
	v_cvt_pk_bf16_f32 v163, v52, v53
	v_mul_f32_e32 v170, 0xbfb8aa3b, v54
	v_mul_f32_e32 v171, 0xbfb8aa3b, v55
	v_mul_f32_e32 v172, 0xbfb8aa3b, v56
	v_mul_f32_e32 v173, 0xbfb8aa3b, v57
	v_exp_f32_e32 v170, v170
	v_exp_f32_e32 v171, v171
	v_exp_f32_e32 v172, v172
	v_exp_f32_e32 v173, v173
	v_add_f32_e32 v170, 1.0, v170
	v_add_f32_e32 v171, 1.0, v171
	v_add_f32_e32 v172, 1.0, v172
	v_add_f32_e32 v173, 1.0, v173
	v_rcp_f32_e32 v170, v170
	v_rcp_f32_e32 v171, v171
	v_rcp_f32_e32 v172, v172
	v_rcp_f32_e32 v173, v173
	s_nop 0
	v_mul_f32_e32 v54, v54, v170
	v_mul_f32_e32 v55, v55, v171
	v_mul_f32_e32 v56, v56, v172
	v_mul_f32_e32 v57, v57, v173
	v_cvt_pk_bf16_f32 v164, v54, v55
	v_cvt_pk_bf16_f32 v165, v56, v57
	global_store_dwordx4 v148, v[162:165], s[8:9]
	s_add_u32 s8, s8, 0xf000
	s_addc_u32 s9, s9, 0
	s_waitcnt lgkmcnt(0)
	v_mul_f32_e32 v170, 0xbfb8aa3b, v58
	v_mul_f32_e32 v171, 0xbfb8aa3b, v59
	v_mul_f32_e32 v172, 0xbfb8aa3b, v60
	v_mul_f32_e32 v173, 0xbfb8aa3b, v61
	v_exp_f32_e32 v170, v170
	v_exp_f32_e32 v171, v171
	v_exp_f32_e32 v172, v172
	v_exp_f32_e32 v173, v173
	v_add_f32_e32 v170, 1.0, v170
	v_add_f32_e32 v171, 1.0, v171
	v_add_f32_e32 v172, 1.0, v172
	v_add_f32_e32 v173, 1.0, v173
	v_rcp_f32_e32 v170, v170
	v_rcp_f32_e32 v171, v171
	v_rcp_f32_e32 v172, v172
	v_rcp_f32_e32 v173, v173
	s_nop 0
	v_mul_f32_e32 v58, v58, v170
	v_mul_f32_e32 v59, v59, v171
	v_mul_f32_e32 v60, v60, v172
	v_mul_f32_e32 v61, v61, v173
	v_cvt_pk_bf16_f32 v166, v58, v59
	v_cvt_pk_bf16_f32 v167, v60, v61
	v_mul_f32_e32 v170, 0xbfb8aa3b, v62
	v_mul_f32_e32 v171, 0xbfb8aa3b, v63
	v_mul_f32_e32 v172, 0xbfb8aa3b, v64
	v_mul_f32_e32 v173, 0xbfb8aa3b, v65
	v_exp_f32_e32 v170, v170
	v_exp_f32_e32 v171, v171
	v_exp_f32_e32 v172, v172
	v_exp_f32_e32 v173, v173
	v_add_f32_e32 v170, 1.0, v170
	v_add_f32_e32 v171, 1.0, v171
	v_add_f32_e32 v172, 1.0, v172
	v_add_f32_e32 v173, 1.0, v173
	v_rcp_f32_e32 v170, v170
	v_rcp_f32_e32 v171, v171
	v_rcp_f32_e32 v172, v172
	v_rcp_f32_e32 v173, v173
	s_nop 0
	v_mul_f32_e32 v62, v62, v170
	v_mul_f32_e32 v63, v63, v171
	v_mul_f32_e32 v64, v64, v172
	v_mul_f32_e32 v65, v65, v173
	v_cvt_pk_bf16_f32 v168, v62, v63
	v_cvt_pk_bf16_f32 v169, v64, v65
	global_store_dwordx4 v148, v[166:169], s[8:9]
	s_add_u32 s8, s8, 0xf000
	s_addc_u32 s9, s9, 0
	ds_write2_b32 v146, v18, v2 offset0:0 offset1:32
	ds_write2_b32 v146, v19, v3 offset0:68 offset1:100
	ds_write2_b32 v146, v20, v4 offset0:136 offset1:168
	ds_write2_b32 v146, v21, v5 offset0:204 offset1:236
	v_add_u32_e32 v146, 0x880, v146
	ds_write2_b32 v146, v22, v6 offset0:0 offset1:32
	ds_write2_b32 v146, v23, v7 offset0:68 offset1:100
	ds_write2_b32 v146, v24, v8 offset0:136 offset1:168
	ds_write2_b32 v146, v25, v9 offset0:204 offset1:236
	v_add_u32_e32 v146, 0x880, v146
	ds_write2_b32 v146, v26, v10 offset0:0 offset1:32
	ds_write2_b32 v146, v27, v11 offset0:68 offset1:100
	ds_write2_b32 v146, v28, v12 offset0:136 offset1:168
	ds_write2_b32 v146, v29, v13 offset0:204 offset1:236
	v_add_u32_e32 v146, 0x880, v146
	ds_write2_b32 v146, v30, v14 offset0:0 offset1:32
	ds_write2_b32 v146, v31, v15 offset0:68 offset1:100
	ds_write2_b32 v146, v32, v16 offset0:136 offset1:168
	ds_write2_b32 v146, v33, v17 offset0:204 offset1:236
	v_subrev_u32_e32 v146, 0x1980, v146
	ds_read_b128 v[2:5], v147
	ds_read_b128 v[6:9], v147 offset:16
	ds_read_b128 v[10:13], v147 offset:2176
	ds_read_b128 v[14:17], v147 offset:2192
	ds_read_b128 v[18:21], v147 offset:4352
	ds_read_b128 v[22:25], v147 offset:4368
	ds_read_b128 v[26:29], v147 offset:6528
	ds_read_b128 v[30:33], v147 offset:6544
	s_waitcnt lgkmcnt(0)
	s_barrier
	v_mul_f32_e32 v170, 0xbfb8aa3b, v2
	v_mul_f32_e32 v171, 0xbfb8aa3b, v3
	v_mul_f32_e32 v172, 0xbfb8aa3b, v4
	v_mul_f32_e32 v173, 0xbfb8aa3b, v5
	v_exp_f32_e32 v170, v170
	v_exp_f32_e32 v171, v171
	v_exp_f32_e32 v172, v172
	v_exp_f32_e32 v173, v173
	v_add_f32_e32 v170, 1.0, v170
	v_add_f32_e32 v171, 1.0, v171
	v_add_f32_e32 v172, 1.0, v172
	v_add_f32_e32 v173, 1.0, v173
	v_rcp_f32_e32 v170, v170
	v_rcp_f32_e32 v171, v171
	v_rcp_f32_e32 v172, v172
	v_rcp_f32_e32 v173, v173
	s_nop 0
	v_mul_f32_e32 v2, v2, v170
	v_mul_f32_e32 v3, v3, v171
	v_mul_f32_e32 v4, v4, v172
	v_mul_f32_e32 v5, v5, v173
	v_cvt_pk_bf16_f32 v154, v2, v3
	v_cvt_pk_bf16_f32 v155, v4, v5
	v_mul_f32_e32 v170, 0xbfb8aa3b, v6
	v_mul_f32_e32 v171, 0xbfb8aa3b, v7
	v_mul_f32_e32 v172, 0xbfb8aa3b, v8
	v_mul_f32_e32 v173, 0xbfb8aa3b, v9
	v_exp_f32_e32 v170, v170
	v_exp_f32_e32 v171, v171
	v_exp_f32_e32 v172, v172
	v_exp_f32_e32 v173, v173
	v_add_f32_e32 v170, 1.0, v170
	v_add_f32_e32 v171, 1.0, v171
	v_add_f32_e32 v172, 1.0, v172
	v_add_f32_e32 v173, 1.0, v173
	v_rcp_f32_e32 v170, v170
	v_rcp_f32_e32 v171, v171
	v_rcp_f32_e32 v172, v172
	v_rcp_f32_e32 v173, v173
	s_nop 0
	v_mul_f32_e32 v6, v6, v170
	v_mul_f32_e32 v7, v7, v171
	v_mul_f32_e32 v8, v8, v172
	v_mul_f32_e32 v9, v9, v173
	v_cvt_pk_bf16_f32 v156, v6, v7
	v_cvt_pk_bf16_f32 v157, v8, v9
	global_store_dwordx4 v148, v[154:157], s[8:9]
	s_add_u32 s8, s8, 0xf000
	s_addc_u32 s9, s9, 0
	v_mul_f32_e32 v170, 0xbfb8aa3b, v10
	v_mul_f32_e32 v171, 0xbfb8aa3b, v11
	v_mul_f32_e32 v172, 0xbfb8aa3b, v12
	v_mul_f32_e32 v173, 0xbfb8aa3b, v13
	v_exp_f32_e32 v170, v170
	v_exp_f32_e32 v171, v171
	v_exp_f32_e32 v172, v172
	v_exp_f32_e32 v173, v173
	v_add_f32_e32 v170, 1.0, v170
	v_add_f32_e32 v171, 1.0, v171
	v_add_f32_e32 v172, 1.0, v172
	v_add_f32_e32 v173, 1.0, v173
	v_rcp_f32_e32 v170, v170
	v_rcp_f32_e32 v171, v171
	v_rcp_f32_e32 v172, v172
	v_rcp_f32_e32 v173, v173
	s_nop 0
	v_mul_f32_e32 v10, v10, v170
	v_mul_f32_e32 v11, v11, v171
	v_mul_f32_e32 v12, v12, v172
	v_mul_f32_e32 v13, v13, v173
	v_cvt_pk_bf16_f32 v158, v10, v11
	v_cvt_pk_bf16_f32 v159, v12, v13
	v_mul_f32_e32 v170, 0xbfb8aa3b, v14
	v_mul_f32_e32 v171, 0xbfb8aa3b, v15
	v_mul_f32_e32 v172, 0xbfb8aa3b, v16
	v_mul_f32_e32 v173, 0xbfb8aa3b, v17
	v_exp_f32_e32 v170, v170
	v_exp_f32_e32 v171, v171
	v_exp_f32_e32 v172, v172
	v_exp_f32_e32 v173, v173
	v_add_f32_e32 v170, 1.0, v170
	v_add_f32_e32 v171, 1.0, v171
	v_add_f32_e32 v172, 1.0, v172
	v_add_f32_e32 v173, 1.0, v173
	v_rcp_f32_e32 v170, v170
	v_rcp_f32_e32 v171, v171
	v_rcp_f32_e32 v172, v172
	v_rcp_f32_e32 v173, v173
	s_nop 0
	v_mul_f32_e32 v14, v14, v170
	v_mul_f32_e32 v15, v15, v171
	v_mul_f32_e32 v16, v16, v172
	v_mul_f32_e32 v17, v17, v173
	v_cvt_pk_bf16_f32 v160, v14, v15
	v_cvt_pk_bf16_f32 v161, v16, v17
	global_store_dwordx4 v148, v[158:161], s[8:9]
	s_add_u32 s8, s8, 0xf000
	s_addc_u32 s9, s9, 0
	v_mul_f32_e32 v170, 0xbfb8aa3b, v18
	v_mul_f32_e32 v171, 0xbfb8aa3b, v19
	v_mul_f32_e32 v172, 0xbfb8aa3b, v20
	v_mul_f32_e32 v173, 0xbfb8aa3b, v21
	v_exp_f32_e32 v170, v170
	v_exp_f32_e32 v171, v171
	v_exp_f32_e32 v172, v172
	v_exp_f32_e32 v173, v173
	v_add_f32_e32 v170, 1.0, v170
	v_add_f32_e32 v171, 1.0, v171
	v_add_f32_e32 v172, 1.0, v172
	v_add_f32_e32 v173, 1.0, v173
	v_rcp_f32_e32 v170, v170
	v_rcp_f32_e32 v171, v171
	v_rcp_f32_e32 v172, v172
	v_rcp_f32_e32 v173, v173
	s_nop 0
	v_mul_f32_e32 v18, v18, v170
	v_mul_f32_e32 v19, v19, v171
	v_mul_f32_e32 v20, v20, v172
	v_mul_f32_e32 v21, v21, v173
	v_cvt_pk_bf16_f32 v162, v18, v19
	v_cvt_pk_bf16_f32 v163, v20, v21
	v_mul_f32_e32 v170, 0xbfb8aa3b, v22
	v_mul_f32_e32 v171, 0xbfb8aa3b, v23
	v_mul_f32_e32 v172, 0xbfb8aa3b, v24
	v_mul_f32_e32 v173, 0xbfb8aa3b, v25
	v_exp_f32_e32 v170, v170
	v_exp_f32_e32 v171, v171
	v_exp_f32_e32 v172, v172
	v_exp_f32_e32 v173, v173
	v_add_f32_e32 v170, 1.0, v170
	v_add_f32_e32 v171, 1.0, v171
	v_add_f32_e32 v172, 1.0, v172
	v_add_f32_e32 v173, 1.0, v173
	v_rcp_f32_e32 v170, v170
	v_rcp_f32_e32 v171, v171
	v_rcp_f32_e32 v172, v172
	v_rcp_f32_e32 v173, v173
	s_nop 0
	v_mul_f32_e32 v22, v22, v170
	v_mul_f32_e32 v23, v23, v171
	v_mul_f32_e32 v24, v24, v172
	v_mul_f32_e32 v25, v25, v173
	v_cvt_pk_bf16_f32 v164, v22, v23
	v_cvt_pk_bf16_f32 v165, v24, v25
	global_store_dwordx4 v148, v[162:165], s[8:9]
	s_add_u32 s8, s8, 0xf000
	s_addc_u32 s9, s9, 0
	v_mul_f32_e32 v170, 0xbfb8aa3b, v26
	v_mul_f32_e32 v171, 0xbfb8aa3b, v27
	v_mul_f32_e32 v172, 0xbfb8aa3b, v28
	v_mul_f32_e32 v173, 0xbfb8aa3b, v29
	v_exp_f32_e32 v170, v170
	v_exp_f32_e32 v171, v171
	v_exp_f32_e32 v172, v172
	v_exp_f32_e32 v173, v173
	v_add_f32_e32 v170, 1.0, v170
	v_add_f32_e32 v171, 1.0, v171
	v_add_f32_e32 v172, 1.0, v172
	v_add_f32_e32 v173, 1.0, v173
	v_rcp_f32_e32 v170, v170
	v_rcp_f32_e32 v171, v171
	v_rcp_f32_e32 v172, v172
	v_rcp_f32_e32 v173, v173
	s_nop 0
	v_mul_f32_e32 v26, v26, v170
	v_mul_f32_e32 v27, v27, v171
	v_mul_f32_e32 v28, v28, v172
	v_mul_f32_e32 v29, v29, v173
	v_cvt_pk_bf16_f32 v166, v26, v27
	v_cvt_pk_bf16_f32 v167, v28, v29
	v_mul_f32_e32 v170, 0xbfb8aa3b, v30
	v_mul_f32_e32 v171, 0xbfb8aa3b, v31
	v_mul_f32_e32 v172, 0xbfb8aa3b, v32
	v_mul_f32_e32 v173, 0xbfb8aa3b, v33
	v_exp_f32_e32 v170, v170
	v_exp_f32_e32 v171, v171
	v_exp_f32_e32 v172, v172
	v_exp_f32_e32 v173, v173
	v_add_f32_e32 v170, 1.0, v170
	v_add_f32_e32 v171, 1.0, v171
	v_add_f32_e32 v172, 1.0, v172
	v_add_f32_e32 v173, 1.0, v173
	v_rcp_f32_e32 v170, v170
	v_rcp_f32_e32 v171, v171
	v_rcp_f32_e32 v172, v172
	v_rcp_f32_e32 v173, v173
	s_nop 0
	v_mul_f32_e32 v30, v30, v170
	v_mul_f32_e32 v31, v31, v171
	v_mul_f32_e32 v32, v32, v172
	v_mul_f32_e32 v33, v33, v173
	v_cvt_pk_bf16_f32 v168, v30, v31
	v_cvt_pk_bf16_f32 v169, v32, v33
	global_store_dwordx4 v148, v[166:169], s[8:9]
	s_add_u32 s8, s8, 0xf000
	s_addc_u32 s9, s9, 0
	s_add_i32 s70, s70, s10
	s_cmp_lt_i32 s70, s71
	s_cbranch_scc0 .LBB0_209
	s_branch .LBB0_215
